# MFMA/LDS interleave: second V-fragment ds_read_b64_tr batch issued with the first (spare VGPRs) so it lands in the first PV MFMA group's shadow; attention branch 1 and last strided branch; on top of v
# baseline (speedup 1.0000x reference)
; #define LAS __attribute__((address_space(3)))
; __device__ __forceinline__ void attn_pair_update(QTile& t0, const int mq0, QTile& t1, const int mq1, int mk0, unsigned VSa, LAS unsigned char* KS, int lane) {
;     ...
;         const bf16x8 a0 = *(const LAS bf16x8*)(KS + ((fr)*HP + 32 * kk + 8 * fq) * 2);
;         const bf16x8 a1 = *(const LAS bf16x8*)(KS + ((16 + fr) * HP + 32 * kk + 8 * fq) * 2);
;         s00 = __builtin_amdgcn_mfma_f32_16x16x32_bf16(a0, t0.q[kk], s00, 0, 0, 0);
;         s01 = __builtin_amdgcn_mfma_f32_16x16x32_bf16(a1, t0.q[kk], s01, 0, 0, 0);
;         s10 = __builtin_amdgcn_mfma_f32_16x16x32_bf16(a0, t1.q[kk], s10, 0, 0, 0);
;         s11 = __builtin_amdgcn_mfma_f32_16x16x32_bf16(a1, t1.q[kk], s11, 0, 0, 0);
;     }
;     const float NEG = -__builtin_inff();
;     float mx0 = NEG, mx1 = NEG;
; #pragma unroll
;     for (int j = 0; j < 4; ++j) {
;         const int mk = mk0 + 4 * fq + j, jd0 = mq0 - mk, jd1 = mq1 - mk;
;         const bool kv0 = (mk >= 0), kv1 = (mk + 16 >= 0);
;         if (!((jd0 >= 0) && (jd0 <= 128) && kv0)) s00[j] = NEG;
;         if (!((jd0 - 16 >= 0) && (jd0 - 16 <= 128) && kv1)) s01[j] = NEG;
;         if (!((jd1 >= 0) && (jd1 <= 128) && kv0)) s10[j] = NEG;
;         if (!((jd1 - 16 >= 0) && (jd1 - 16 <= 128) && kv1)) s11[j] = NEG;
;         mx0 = fmaxf(mx0, fmaxf(s00[j], s01[j])); mx1 = fmaxf(mx1, fmaxf(s10[j], s11[j]));
;     }
.LBB0_782:
	v_add3_u32 v2, s17, v198, v199
	ds_read_b128 v[120:123], v2
	ds_read_b128 v[124:127], v2 offset:64
	ds_read_b128 v[132:135], v2 offset:4352
	ds_read_b128 v[136:139], v2 offset:4416
	v_add_u32_e32 v3, s13, v117
	v_cmp_lt_i32_e32 vcc, -1, v118
	s_waitcnt lgkmcnt(3)
	v_mfma_f32_16x16x32_bf16 v[128:131], v[120:123], v[8:11], 0
	v_cmp_lt_i32_e64 s[4:5], s52, v118
	v_add_u32_e32 v110, 0x90, v3
	s_waitcnt lgkmcnt(1)
	v_mfma_f32_16x16x32_bf16 v[140:143], v[132:135], v[8:11], 0
	v_mfma_f32_16x16x32_bf16 v[120:123], v[120:123], v[36:39], 0
	v_mfma_f32_16x16x32_bf16 v[132:135], v[132:135], v[36:39], 0
	v_mfma_f32_16x16x32_bf16 v[128:131], v[124:127], v[16:19], v[128:131]
	s_waitcnt lgkmcnt(0)
	v_mfma_f32_16x16x32_bf16 v[140:143], v[136:139], v[16:19], v[140:143]
	v_mfma_f32_16x16x32_bf16 v[120:123], v[124:127], v[44:47], v[120:123]
	v_mfma_f32_16x16x32_bf16 v[124:127], v[136:139], v[44:47], v[132:135]
	s_nop 2
	ds_read_b128 v[132:135], v2 offset:128
	ds_read_b128 v[136:139], v2 offset:192
	ds_read_b128 v[144:147], v2 offset:4480
	ds_read_b128 v[148:151], v2 offset:4544
	v_add_u32_e32 v2, 0x80, v3
	s_waitcnt lgkmcnt(3)
	v_mfma_f32_16x16x32_bf16 v[128:131], v[132:135], v[20:23], v[128:131]
	v_cmp_gt_u32_e64 s[6:7], s53, v2
	v_mov_b32_e32 v2, s55
	s_and_b64 s[8:9], vcc, s[6:7]
	s_waitcnt lgkmcnt(1)
	v_mfma_f32_16x16x32_bf16 v[140:143], v[144:147], v[20:23], v[140:143]
	v_mfma_f32_16x16x32_bf16 v[128:131], v[136:139], v[24:27], v[128:131]
	v_mfma_f32_16x16x32_bf16 v[120:123], v[132:135], v[52:55], v[120:123]
	v_mfma_f32_16x16x32_bf16 v[124:127], v[144:147], v[52:55], v[124:127]
	s_nop 5
	v_cndmask_b32_e64 v111, v2, v128, s[8:9]
	v_add_u32_e32 v2, 0x70, v3
	v_cmp_gt_u32_e64 s[8:9], s53, v2
	s_waitcnt lgkmcnt(0)
	v_mfma_f32_16x16x32_bf16 v[132:135], v[148:151], v[24:27], v[140:143]
	v_mov_b32_e32 v2, s55
	s_and_b64 s[8:9], s[4:5], s[8:9]
	v_add_u32_e32 v128, 0x6f, v3
	v_mfma_f32_16x16x32_bf16 v[120:123], v[136:139], v[56:59], v[120:123]
	v_mfma_f32_16x16x32_bf16 v[124:127], v[148:151], v[56:59], v[124:127]
	s_nop 2
	v_cndmask_b32_e64 v113, v2, v132, s[8:9]
	v_cmp_gt_u32_e64 s[8:9], s53, v110
	s_and_b64 vcc, vcc, s[8:9]
	s_nop 0
	v_cndmask_b32_e32 v114, v2, v120, vcc
	s_and_b64 vcc, s[4:5], s[6:7]
	v_cndmask_b32_e32 v115, v2, v124, vcc
	v_max_f32_e32 v2, v113, v113
	v_max_f32_e32 v110, v111, v111
	v_max_f32_e32 v2, v110, v2
	v_max_f32_e32 v110, v115, v115
	v_max_f32_e32 v120, v114, v114
	v_max_f32_e32 v110, v120, v110
	v_add_u32_e32 v120, 0x7f, v3
	v_cmp_lt_i32_e32 vcc, -2, v118
	v_cmp_gt_u32_e64 s[6:7], s53, v120
	s_and_b64 s[8:9], vcc, s[6:7]
	v_cmp_lt_i32_e64 s[4:5], s56, v118
	v_cndmask_b32_e64 v120, v214, v129, s[8:9]
	v_cmp_gt_u32_e64 s[8:9], s53, v128
	v_add_u32_e32 v124, 0x8f, v3
	s_and_b64 s[8:9], s[4:5], s[8:9]
	v_cndmask_b32_e64 v128, v214, v133, s[8:9]
	v_cmp_gt_u32_e64 s[8:9], s53, v124
	s_and_b64 vcc, vcc, s[8:9]
	v_cndmask_b32_e32 v124, v214, v121, vcc
	s_and_b64 vcc, s[4:5], s[6:7]
	v_cndmask_b32_e32 v129, v214, v125, vcc
	v_max_f32_e32 v121, v128, v128
	v_max_f32_e32 v125, v120, v120
	v_max_f32_e32 v121, v125, v121
	v_max3_f32 v2, v2, s55, v121
	v_max_f32_e32 v121, v129, v129
	v_max_f32_e32 v125, v124, v124
	v_max_f32_e32 v121, v125, v121
	v_max3_f32 v110, v110, s55, v121
	v_add_u32_e32 v121, 0x7e, v3
	v_cmp_lt_i32_e32 vcc, -3, v118
	v_cmp_gt_u32_e64 s[6:7], s53, v121
	s_and_b64 s[8:9], vcc, s[6:7]
	v_add_u32_e32 v121, 0x6e, v3
	v_cmp_lt_i32_e64 s[4:5], s57, v118
	v_cndmask_b32_e64 v130, v214, v130, s[8:9]
	v_cmp_gt_u32_e64 s[8:9], s53, v121
	v_add_u32_e32 v125, 0x8e, v3
	s_and_b64 s[8:9], s[4:5], s[8:9]
	v_cndmask_b32_e64 v132, v214, v134, s[8:9]
	v_cmp_gt_u32_e64 s[8:9], s53, v125
	s_and_b64 vcc, vcc, s[8:9]
	v_cndmask_b32_e32 v122, v214, v122, vcc
	s_and_b64 vcc, s[4:5], s[6:7]
	v_cndmask_b32_e32 v133, v214, v126, vcc
	v_max_f32_e32 v121, v132, v132
	v_max_f32_e32 v125, v130, v130
	v_max_f32_e32 v121, v125, v121
	v_max_f32_e32 v125, v133, v133
	v_max_f32_e32 v126, v122, v122
	v_max_f32_e32 v125, v126, v125
	v_add_u32_e32 v126, 0x7d, v3
	v_cmp_lt_i32_e32 vcc, -4, v118
	v_cmp_gt_u32_e64 s[6:7], s53, v126
	v_add_u32_e32 v134, 0x8d, v3
	s_and_b64 s[8:9], vcc, s[6:7]
	v_add_u32_e32 v3, 0x6d, v3
	v_cmp_lt_i32_e64 s[4:5], s58, v118
	v_cndmask_b32_e64 v131, v214, v131, s[8:9]
	v_cmp_gt_u32_e64 s[8:9], s53, v3
	s_and_b64 s[8:9], s[4:5], s[8:9]
	s_nop 0
	v_cndmask_b32_e64 v3, v214, v135, s[8:9]
	v_cmp_gt_u32_e64 s[8:9], s53, v134
	s_and_b64 vcc, vcc, s[8:9]
	v_cndmask_b32_e32 v123, v214, v123, vcc
	s_and_b64 vcc, s[4:5], s[6:7]
	v_cndmask_b32_e32 v134, v214, v127, vcc
	v_max_f32_e32 v126, v3, v3
	v_max_f32_e32 v127, v131, v131
	v_max_f32_e32 v126, v127, v126
	v_max3_f32 v2, v2, v121, v126
	v_max_f32_e32 v121, v134, v134
	v_max_f32_e32 v126, v123, v123
	v_max_f32_e32 v121, v126, v121
	v_max3_f32 v110, v110, v125, v121
	s_add_i32 s4, s17, 0x2200
	v_mov_b32_e32 v121, v110
	v_mov_b32_e32 v135, v2
	s_waitcnt lgkmcnt(0)
; __device__ __forceinline__ bf16x8 pack8(f32x4 a, f32x4 b) { u32x4 w; w.x = pk2(a[0], a[1]); w.y = pk2(a[2], a[3]); w.z = pk2(b[0], b[1]); w.w = pk2(b[2], b[3]); return __builtin_bit_cast(bf16x8, w); }
; __device__ __forceinline__ void attn_pair_update(QTile& t0, const int mq0, QTile& t1, const int mq1, int mk0, unsigned VSa, LAS unsigned char* KS, int lane) {
;     ...
;     { const float a = __shfl_xor(mx0, 16), b = __shfl_xor(mx1, 16); mx0 = fmaxf(mx0, a); mx1 = fmaxf(mx1, b); }
;     { const float a = __shfl_xor(mx0, 32), b = __shfl_xor(mx1, 32); mx0 = fmaxf(mx0, a); mx1 = fmaxf(mx1, b); }
;     const float mn0 = fmaxf(t0.m, mx0), mn1 = fmaxf(t1.m, mx1);
;     const float mu0 = (mn0 == NEG) ? 0.f : mn0, mu1 = (mn1 == NEG) ? 0.f : mn1;
;     const float al0 = __expf(t0.m - mu0), al1 = __expf(t1.m - mu1);
;     f32x4 p00, p01, p10, p11; float ps0 = 0.f, ps1 = 0.f;
; #pragma unroll
;     for (int j = 0; j < 4; ++j) {
;         p00[j] = __expf(s00[j] - mu0); p01[j] = __expf(s01[j] - mu0); p10[j] = __expf(s10[j] - mu1); p11[j] = __expf(s11[j] - mu1);
;         ps0 += p00[j] + p01[j]; ps1 += p10[j] + p11[j];
;     }
;     t0.l = t0.l * al0 + ps0; t0.m = mn0; t1.l = t1.l * al1 + ps1; t1.m = mn1;
; #pragma unroll
;     for (int dt = 0; dt < 8; ++dt) { t0.o[dt] *= al0; t1.o[dt] *= al1; }
;     const bf16x8 pf0 = pack8(p00, p01), pf1 = pack8(p10, p11);
;     const unsigned vb = VSa + (unsigned)(((4 * fq + (fr >> 2)) * HP + 4 * (fr & 3)) * 2);
;     s16x4 ra[8];
;     TR8(ra, vb, 0);
; #pragma unroll
;     for (int dt = 0; dt < 4; ++dt) { const bf16x8 vf = cat8(ra[2 * dt], ra[2 * dt + 1]);
	s_nop 0
	v_permlane16_swap_b32_e32 v121, v110
	v_permlane16_swap_b32_e32 v135, v2
	v_max_f32_e32 v121, v110, v121
	v_max_f32_e32 v2, v2, v135
	v_mov_b32_e32 v126, v121
	v_mov_b32_e32 v125, v2
	v_mov_b32_e32 v127, v1
	s_nop 0
	v_permlane32_swap_b32_e32 v126, v121
	v_permlane32_swap_b32_e32 v125, v2
	v_max3_f32 v110, v112, v2, v125
	v_cmp_neq_f32_e32 vcc, s55, v110
	v_max3_f32 v2, v0, v121, v126
	v_cndmask_b32_e32 v135, 0, v110, vcc
	v_sub_f32_e32 v112, v112, v135
	v_cmp_neq_f32_e32 vcc, s55, v2
	v_mul_f32_e32 v137, 0x3fb8aa3b, v112
	v_sub_f32_e32 v112, v113, v135
	v_cndmask_b32_e32 v136, 0, v2, vcc
	v_mul_f32_e32 v112, 0x3fb8aa3b, v112
	v_exp_f32_e32 v138, v112
	v_sub_f32_e32 v112, v114, v136
	v_mul_f32_e32 v112, 0x3fb8aa3b, v112
	v_exp_f32_e32 v139, v112
	v_sub_f32_e32 v112, v115, v136
	v_sub_f32_e32 v0, v0, v136
	v_mul_f32_e32 v112, 0x3fb8aa3b, v112
	v_mul_f32_e32 v140, 0x3fb8aa3b, v0
	v_sub_f32_e32 v0, v120, v135
	v_sub_f32_e32 v111, v111, v135
	v_exp_f32_e32 v145, v112
	v_mul_f32_e32 v0, 0x3fb8aa3b, v0
	v_sub_f32_e32 v112, v124, v136
	v_mul_f32_e32 v111, 0x3fb8aa3b, v111
	v_exp_f32_e32 v120, v0
	v_sub_f32_e32 v0, v128, v135
	v_mul_f32_e32 v112, 0x3fb8aa3b, v112
	v_exp_f32_e32 v111, v111
	v_mul_f32_e32 v0, 0x3fb8aa3b, v0
	v_exp_f32_e32 v124, v112
	v_sub_f32_e32 v112, v129, v136
	v_exp_f32_e32 v0, v0
	v_mul_f32_e32 v112, 0x3fb8aa3b, v112
	v_exp_f32_e32 v126, v112
	v_add_f32_e32 v121, v111, v138
	v_add_f32_e32 v125, v139, v145
	v_pk_add_f32 v[112:113], v[120:121], v[0:1]
	v_sub_f32_e32 v3, v3, v135
	v_pk_add_f32 v[114:115], v[112:113], v[112:113] op_sel_hi:[0,1]
	v_pk_add_f32 v[112:113], v[124:125], v[126:127]
	v_mul_f32_e32 v3, 0x3fb8aa3b, v3
	v_pk_add_f32 v[112:113], v[112:113], v[112:113] op_sel_hi:[0,1]
	v_sub_f32_e32 v112, v130, v135
	v_mul_f32_e32 v112, 0x3fb8aa3b, v112
	v_exp_f32_e32 v147, v112
	v_sub_f32_e32 v112, v132, v135
	v_mul_f32_e32 v112, 0x3fb8aa3b, v112
	v_exp_f32_e32 v149, v112
	v_sub_f32_e32 v112, v122, v136
	v_mul_f32_e32 v112, 0x3fb8aa3b, v112
	v_exp_f32_e32 v151, v112
	v_sub_f32_e32 v112, v133, v136
	v_exp_f32_e32 v114, v3
	v_sub_f32_e32 v3, v123, v136
	v_mul_f32_e32 v112, 0x3fb8aa3b, v112
	v_mul_f32_e32 v3, 0x3fb8aa3b, v3
	v_exp_f32_e32 v152, v112
	v_sub_f32_e32 v112, v131, v135
	v_exp_f32_e32 v146, v3
	v_sub_f32_e32 v3, v134, v136
	v_mul_f32_e32 v112, 0x3fb8aa3b, v112
	v_mul_f32_e32 v3, 0x3fb8aa3b, v3
	v_exp_f32_e32 v144, v112
	v_exp_f32_e32 v148, v137
	v_exp_f32_e32 v150, v140
	v_exp_f32_e32 v112, v3
	v_cvt_pk_bf16_f32 v120, v111, v120
	v_pk_mul_f32 v[106:107], v[106:107], v[148:149] op_sel_hi:[1,0]
	v_pk_mul_f32 v[104:105], v[104:105], v[148:149] op_sel_hi:[1,0]
	v_pk_mul_f32 v[102:103], v[102:103], v[150:151] op_sel_hi:[1,0]
	v_pk_mul_f32 v[100:101], v[100:101], v[150:151] op_sel_hi:[1,0]
	v_cvt_pk_bf16_f32 v121, v147, v144
	v_cvt_pk_bf16_f32 v122, v138, v0
	v_cvt_pk_bf16_f32 v123, v149, v114
	v_cvt_pk_bf16_f32 v124, v139, v124
	v_add_u32_e32 v0, s4, v200
	ds_read_b64_tr_b16 v[140:141], v0 offset:0+0
	ds_read_b64_tr_b16 v[142:143], v0 offset:0+4352
	ds_read_b64_tr_b16 v[136:137], v0 offset:0+32
	ds_read_b64_tr_b16 v[138:139], v0 offset:0+4384
	ds_read_b64_tr_b16 v[132:133], v0 offset:0+64
	ds_read_b64_tr_b16 v[134:135], v0 offset:0+4416
	ds_read_b64_tr_b16 v[128:129], v0 offset:0+96
	ds_read_b64_tr_b16 v[130:131], v0 offset:0+4448
	ds_read_b64_tr_b16 v[248:249], v0 offset:128+0
	ds_read_b64_tr_b16 v[250:251], v0 offset:128+4352
	ds_read_b64_tr_b16 v[244:245], v0 offset:128+32
	ds_read_b64_tr_b16 v[246:247], v0 offset:128+4384
	ds_read_b64_tr_b16 v[240:241], v0 offset:128+64
	ds_read_b64_tr_b16 v[242:243], v0 offset:128+4416
	ds_read_b64_tr_b16 v[236:237], v0 offset:128+96
	ds_read_b64_tr_b16 v[238:239], v0 offset:128+4448
	s_waitcnt lgkmcnt(8)
; __device__ __forceinline__ bf16x8 pack8(f32x4 a, f32x4 b) { u32x4 w; w.x = pk2(a[0], a[1]); w.y = pk2(a[2], a[3]); w.z = pk2(b[0], b[1]); w.w = pk2(b[2], b[3]); return __builtin_bit_cast(bf16x8, w); }
; __device__ __forceinline__ void attn_pair_update(QTile& t0, const int mq0, QTile& t1, const int mq1, int mk0, unsigned VSa, LAS unsigned char* KS, int lane) {
;     ...
;     t0.l = t0.l * al0 + ps0; t0.m = mn0; t1.l = t1.l * al1 + ps1; t1.m = mn1;
; #pragma unroll
;     for (int dt = 0; dt < 8; ++dt) { t0.o[dt] *= al0; t1.o[dt] *= al1; }
;     const bf16x8 pf0 = pack8(p00, p01), pf1 = pack8(p10, p11);
;     const unsigned vb = VSa + (unsigned)(((4 * fq + (fr >> 2)) * HP + 4 * (fr & 3)) * 2);
;     s16x4 ra[8];
;     TR8(ra, vb, 0);
; #pragma unroll
;     for (int dt = 0; dt < 4; ++dt) { const bf16x8 vf = cat8(ra[2 * dt], ra[2 * dt + 1]);
;         t0.o[dt] = __builtin_amdgcn_mfma_f32_16x16x32_bf16(vf, pf0, t0.o[dt], 0, 0, 0); t1.o[dt] = __builtin_amdgcn_mfma_f32_16x16x32_bf16(vf, pf1, t1.o[dt], 0, 0, 0); }
;     s16x4 rb[8];
;     TR8(rb, vb, 128);
; #pragma unroll
;     for (int dt = 0; dt < 4; ++dt) { const bf16x8 vf = cat8(rb[2 * dt], rb[2 * dt + 1]);
;         t0.o[4 + dt] = __builtin_amdgcn_mfma_f32_16x16x32_bf16(vf, pf0, t0.o[4 + dt], 0, 0, 0); t1.o[4 + dt] = __builtin_amdgcn_mfma_f32_16x16x32_bf16(vf, pf1, t1.o[4 + dt], 0, 0, 0); }
	v_cvt_pk_bf16_f32 v125, v151, v146
	v_cvt_pk_bf16_f32 v126, v145, v126
	v_cvt_pk_bf16_f32 v127, v152, v112
	v_pk_mul_f32 v[98:99], v[98:99], v[148:149] op_sel_hi:[1,0]
	v_pk_mul_f32 v[96:97], v[96:97], v[148:149] op_sel_hi:[1,0]
	v_pk_mul_f32 v[62:63], v[62:63], v[150:151] op_sel_hi:[1,0]
	v_pk_mul_f32 v[60:61], v[60:61], v[150:151] op_sel_hi:[1,0]
	v_pk_mul_f32 v[90:91], v[90:91], v[148:149] op_sel_hi:[1,0]
	v_pk_mul_f32 v[88:89], v[88:89], v[148:149] op_sel_hi:[1,0]
	v_add_f32_e32 v145, v147, v149
	v_pk_mul_f32 v[50:51], v[50:51], v[150:151] op_sel_hi:[1,0]
	v_pk_mul_f32 v[48:49], v[48:49], v[150:151] op_sel_hi:[1,0]
	v_pk_mul_f32 v[86:87], v[86:87], v[148:149] op_sel_hi:[1,0]
	v_pk_mul_f32 v[84:85], v[84:85], v[148:149] op_sel_hi:[1,0]
	v_pk_mul_f32 v[42:43], v[42:43], v[150:151] op_sel_hi:[1,0]
	v_pk_mul_f32 v[40:41], v[40:41], v[150:151] op_sel_hi:[1,0]
	v_pk_mul_f32 v[78:79], v[78:79], v[148:149] op_sel_hi:[1,0]
	v_pk_mul_f32 v[76:77], v[76:77], v[148:149] op_sel_hi:[1,0]
	v_add_f32_e32 v147, v151, v152
	v_pk_mul_f32 v[34:35], v[34:35], v[150:151] op_sel_hi:[1,0]
	v_pk_mul_f32 v[32:33], v[32:33], v[150:151] op_sel_hi:[1,0]
	v_pk_mul_f32 v[74:75], v[74:75], v[148:149] op_sel_hi:[1,0]
	v_pk_mul_f32 v[72:73], v[72:73], v[148:149] op_sel_hi:[1,0]
	v_pk_mul_f32 v[30:31], v[30:31], v[150:151] op_sel_hi:[1,0]
	v_pk_mul_f32 v[28:29], v[28:29], v[150:151] op_sel_hi:[1,0]
	v_pk_mul_f32 v[70:71], v[70:71], v[148:149] op_sel_hi:[1,0]
	v_pk_mul_f32 v[68:69], v[68:69], v[148:149] op_sel_hi:[1,0]
	v_pk_mul_f32 v[14:15], v[14:15], v[150:151] op_sel_hi:[1,0]
	v_pk_mul_f32 v[12:13], v[12:13], v[150:151] op_sel_hi:[1,0]
	v_pk_mul_f32 v[66:67], v[66:67], v[148:149] op_sel_hi:[1,0]
	v_pk_mul_f32 v[64:65], v[64:65], v[148:149] op_sel_hi:[1,0]
	v_pk_mul_f32 v[6:7], v[6:7], v[150:151] op_sel_hi:[1,0]
	v_pk_mul_f32 v[4:5], v[4:5], v[150:151] op_sel_hi:[1,0]
	v_mfma_f32_16x16x32_bf16 v[104:107], v[140:143], v[120:123], v[104:107]
	v_add_f32_e64 v114, v144, v114
	v_add_f32_e64 v115, v145, v115
	v_pk_add_f32 v[112:113], v[146:147], v[112:113]
	v_add_f32_e32 v3, v114, v115
	v_mfma_f32_16x16x32_bf16 v[100:103], v[140:143], v[124:127], v[100:103]
	v_add_f32_e32 v111, v112, v113
	v_fmac_f32_e32 v3, v119, v148
	v_fmac_f32_e32 v111, v116, v150
	v_mfma_f32_16x16x32_bf16 v[96:99], v[136:139], v[120:123], v[96:99]
	v_mov_b32_e32 v116, v111
	v_mov_b32_e32 v112, v110
	v_mov_b32_e32 v119, v3
	v_mfma_f32_16x16x32_bf16 v[60:63], v[136:139], v[124:127], v[60:63]
	v_mfma_f32_16x16x32_bf16 v[88:91], v[132:135], v[120:123], v[88:91]
	v_mfma_f32_16x16x32_bf16 v[48:51], v[132:135], v[124:127], v[48:51]
	v_mfma_f32_16x16x32_bf16 v[84:87], v[128:131], v[120:123], v[84:87]
	v_mfma_f32_16x16x32_bf16 v[40:43], v[128:131], v[124:127], v[40:43]
	s_waitcnt lgkmcnt(0)
	v_mov_b32_e32 v0, v2
	v_mfma_f32_16x16x32_bf16 v[76:79], v[248:251], v[120:123], v[76:79]
	v_mfma_f32_16x16x32_bf16 v[32:35], v[248:251], v[124:127], v[32:35]
	v_mfma_f32_16x16x32_bf16 v[72:75], v[244:247], v[120:123], v[72:75]
	v_mfma_f32_16x16x32_bf16 v[28:31], v[244:247], v[124:127], v[28:31]
	v_mfma_f32_16x16x32_bf16 v[68:71], v[240:243], v[120:123], v[68:71]
	v_mfma_f32_16x16x32_bf16 v[12:15], v[240:243], v[124:127], v[12:15]
	v_mfma_f32_16x16x32_bf16 v[64:67], v[236:239], v[120:123], v[64:67]
	v_mfma_f32_16x16x32_bf16 v[4:7], v[236:239], v[124:127], v[4:7]

; #define LAS __attribute__((address_space(3)))
; __device__ __forceinline__ void attn_tile_update(QTile& t, const int mq, int mk0, unsigned VSa, LAS unsigned char* KS, int lane) {
;     ...
;         const bf16x8 a0 = *(const LAS bf16x8*)(KS + ((fr)*HP + 32 * kk + 8 * fq) * 2);
;         const bf16x8 a1 = *(const LAS bf16x8*)(KS + ((16 + fr) * HP + 32 * kk + 8 * fq) * 2);
;         s0 = __builtin_amdgcn_mfma_f32_16x16x32_bf16(a0, t.q[kk], s0, 0, 0, 0);
;         s1 = __builtin_amdgcn_mfma_f32_16x16x32_bf16(a1, t.q[kk], s1, 0, 0, 0);
;     }
;     const float NEG = -__builtin_inff();
;     float mx = NEG;
;     bool v0[4], v1[4];
; #pragma unroll
;     for (int j = 0; j < 4; ++j) {
;         const int mk = mk0 + 4 * fq + j, jd = mq - mk;
;         v0[j] = (jd >= 0) && (jd <= 128) && (mk >= 0);
;         v1[j] = (jd - 16 >= 0) && (jd - 16 <= 128) && (mk + 16 >= 0);
;         if (v0[j]) mx = fmaxf(mx, s0[j]);
;         if (v1[j]) mx = fmaxf(mx, s1[j]);
;     }
;     mx = fmaxf(mx, __shfl_xor(mx, 16)); mx = fmaxf(mx, __shfl_xor(mx, 32));
.LBB0_809:
	ds_read_b128 v[150:153], v223
	ds_read_b128 v[154:157], v223 offset:64
	ds_read_b128 v[158:161], v223 offset:4352
	ds_read_b128 v[184:187], v223 offset:4416
	v_add_u32_e32 v0, s46, v147
	v_add_u32_e32 v149, 0x90, v0
	s_waitcnt lgkmcnt(3)
	v_mfma_f32_16x16x32_bf16 v[150:153], v[150:153], v[2:5], 0
	v_cmp_lt_i32_e32 vcc, -1, v146
	v_cmp_gt_u32_e64 s[6:7], s53, v149
	s_and_b64 vcc, vcc, s[6:7]
	s_waitcnt lgkmcnt(1)
	v_mfma_f32_16x16x32_bf16 v[158:161], v[158:161], v[2:5], 0
	v_cmp_lt_i32_e64 s[4:5], s52, v146
	v_cmp_lt_i32_e64 s[12:13], s56, v146
	v_cmp_lt_i32_e64 s[16:17], s57, v146
	v_mfma_f32_16x16x32_bf16 v[150:153], v[154:157], v[6:9], v[150:153]
	ds_read_b128 v[154:157], v223 offset:128
	ds_read_b128 v[188:191], v223 offset:192
	v_cmp_lt_i32_e64 s[20:21], s58, v146
	s_sub_i32 s46, s46, 32
	s_waitcnt lgkmcnt(2)
	v_mfma_f32_16x16x32_bf16 v[158:161], v[184:187], v[6:9], v[158:161]
	ds_read_b128 v[184:187], v223 offset:4480
	ds_read_b128 v[192:195], v223 offset:4544
	s_add_i32 s44, s44, 1
	v_add_u32_e32 v148, 32, v148
	s_waitcnt lgkmcnt(3)
	v_mfma_f32_16x16x32_bf16 v[150:153], v[154:157], v[10:13], v[150:153]
	v_add_u32_e32 v154, 0x80, v0
	v_cmp_gt_u32_e64 s[8:9], s53, v154
	s_and_b64 s[4:5], s[8:9], s[4:5]
	s_waitcnt lgkmcnt(1)
	v_mfma_f32_16x16x32_bf16 v[154:157], v[184:187], v[10:13], v[158:161]
	v_cmp_lt_i32_e64 s[8:9], -2, v146
	v_mfma_f32_16x16x32_bf16 v[150:153], v[188:191], v[14:17], v[150:153]
	s_waitcnt lgkmcnt(0)
	v_mfma_f32_16x16x32_bf16 v[154:157], v[192:195], v[14:17], v[154:157]
	s_nop 5
	v_max_f32_e32 v149, v150, v150
	v_max_f32_e32 v149, 0xff800000, v149
	v_cndmask_b32_e32 v149, v214, v149, vcc
	v_max_f32_e32 v158, v154, v154
	v_max_f32_e32 v158, v149, v158
	v_cndmask_b32_e64 v149, v149, v158, s[4:5]
	v_add_u32_e32 v158, 0x8f, v0
	v_cmp_gt_u32_e64 s[6:7], s53, v158
	v_add_u32_e32 v158, 0x7f, v0
	v_cmp_gt_u32_e64 s[10:11], s53, v158
	v_max_f32_e32 v158, v151, v151
	v_max_f32_e32 v158, v149, v158
	s_and_b64 s[6:7], s[8:9], s[6:7]
	v_cndmask_b32_e64 v149, v149, v158, s[6:7]
	v_max_f32_e32 v158, v155, v155
	v_max_f32_e32 v158, v149, v158
	s_and_b64 s[8:9], s[10:11], s[12:13]
	v_cndmask_b32_e64 v149, v149, v158, s[8:9]
	v_add_u32_e32 v158, 0x8e, v0
	v_cmp_gt_u32_e64 s[10:11], s53, v158
	v_add_u32_e32 v158, 0x7e, v0
	v_cmp_lt_i32_e64 s[12:13], -3, v146
	v_cmp_gt_u32_e64 s[14:15], s53, v158
	v_max_f32_e32 v158, v152, v152
	v_max_f32_e32 v158, v149, v158
	s_and_b64 s[10:11], s[12:13], s[10:11]
	v_cndmask_b32_e64 v149, v149, v158, s[10:11]
	v_max_f32_e32 v158, v149, v149
	v_max_f32_e32 v159, v156, v156
	v_max_f32_e32 v158, v158, v159
	s_and_b64 s[12:13], s[14:15], s[16:17]
	v_cndmask_b32_e64 v149, v149, v158, s[12:13]
	v_add_u32_e32 v158, 0x8d, v0
	v_add_u32_e32 v0, 0x7d, v0
	v_cmp_gt_u32_e64 s[14:15], s53, v158
	v_cmp_lt_i32_e64 s[16:17], -4, v146
	v_cmp_gt_u32_e64 s[18:19], s53, v0
	v_max_f32_e32 v0, v149, v149
	v_max_f32_e32 v158, v153, v153
	v_max_f32_e32 v0, v0, v158
	s_and_b64 s[14:15], s[16:17], s[14:15]
	v_cndmask_b32_e64 v0, v149, v0, s[14:15]
	v_max_f32_e32 v149, v0, v0
	v_max_f32_e32 v158, v157, v157
	v_max_f32_e32 v149, v149, v158
	s_and_b64 s[16:17], s[18:19], s[20:21]
	v_cndmask_b32_e64 v0, v0, v149, s[16:17]
	v_max_f32_e32 v0, v0, v0
	v_add_u32_e32 v146, 32, v146
	s_cmp_lt_u32 s44, 4
	v_mov_b32_e32 v149, v0
	s_waitcnt lgkmcnt(0)
; __device__ __forceinline__ bf16x8 pack8(f32x4 a, f32x4 b) { u32x4 w; w.x = pk2(a[0], a[1]); w.y = pk2(a[2], a[3]); w.z = pk2(b[0], b[1]); w.w = pk2(b[2], b[3]); return __builtin_bit_cast(bf16x8, w); }
; __device__ __forceinline__ void attn_tile_update(QTile& t, const int mq, int mk0, unsigned VSa, LAS unsigned char* KS, int lane) {
;     ...
;     mx = fmaxf(mx, __shfl_xor(mx, 16)); mx = fmaxf(mx, __shfl_xor(mx, 32));
;     const float mnew = fmaxf(t.m, mx);
;     const float muse = (mnew == NEG) ? 0.f : mnew;
;     const float alpha = __expf(t.m - muse);
;     f32x4 p0, p1; float ps = 0.f;
; #pragma unroll
;     for (int j = 0; j < 4; ++j) { p0[j] = v0[j] ? __expf(s0[j] - muse) : 0.f; p1[j] = v1[j] ? __expf(s1[j] - muse) : 0.f; ps += p0[j] + p1[j]; }
;     t.l = t.l * alpha + ps; t.m = mnew;
; #pragma unroll
;     for (int dt = 0; dt < 8; ++dt) t.o[dt] *= alpha;
;     const bf16x8 pf = pack8(p0, p1);
;     const unsigned vb = VSa + (unsigned)(((4 * fq + (fr >> 2)) * HP + 4 * (fr & 3)) * 2);
;     s16x4 ra[8], rb[8];
;     TR8(ra, vb, 0);
;     TR8(rb, vb, 128);
; #pragma unroll
;     for (int dt = 0; dt < 4; ++dt) t.o[dt] = __builtin_amdgcn_mfma_f32_16x16x32_bf16(cat8(ra[2 * dt], ra[2 * dt + 1]), pf, t.o[dt], 0, 0, 0);
; #pragma unroll
;     for (int dt = 0; dt < 4; ++dt) t.o[4 + dt] = __builtin_amdgcn_mfma_f32_16x16x32_bf16(cat8(rb[2 * dt], rb[2 * dt + 1]), pf, t.o[4 + dt], 0, 0, 0);
	s_nop 0
	v_permlane16_swap_b32_e32 v149, v0
	v_max_f32_e32 v0, v0, v149
	v_mov_b32_e32 v149, v0
	s_nop 1
	v_permlane32_swap_b32_e32 v149, v0
	v_max3_f32 v0, v227, v0, v149
	v_cmp_neq_f32_e64 s[18:19], s55, v0
	s_nop 1
	v_cndmask_b32_e64 v149, 0, v0, s[18:19]
	v_sub_f32_e32 v150, v150, v149
	v_sub_f32_e32 v154, v154, v149
	v_mul_f32_e32 v150, 0x3fb8aa3b, v150
	v_mul_f32_e32 v154, 0x3fb8aa3b, v154
	v_sub_f32_e32 v151, v151, v149
	v_sub_f32_e32 v155, v155, v149
	v_sub_f32_e32 v152, v152, v149
	v_sub_f32_e32 v156, v156, v149
	v_exp_f32_e32 v150, v150
	v_exp_f32_e32 v154, v154
	v_sub_f32_e32 v158, v227, v149
	v_mul_f32_e32 v151, 0x3fb8aa3b, v151
	v_mul_f32_e32 v155, 0x3fb8aa3b, v155
	v_mul_f32_e32 v152, 0x3fb8aa3b, v152
	v_mul_f32_e32 v156, 0x3fb8aa3b, v156
	v_sub_f32_e32 v153, v153, v149
	v_sub_f32_e32 v149, v157, v149
	v_exp_f32_e32 v151, v151
	v_exp_f32_e32 v155, v155
	v_exp_f32_e32 v152, v152
	v_exp_f32_e32 v156, v156
	v_mul_f32_e32 v153, 0x3fb8aa3b, v153
	v_mul_f32_e32 v149, 0x3fb8aa3b, v149
	v_mul_f32_e32 v158, 0x3fb8aa3b, v158
	v_exp_f32_e32 v153, v153
	v_exp_f32_e32 v149, v149
	v_exp_f32_e32 v192, v158
	v_cndmask_b32_e32 v150, 0, v150, vcc
	v_cndmask_b32_e64 v154, 0, v154, s[4:5]
	v_add_f32_e32 v159, v150, v154
	v_cndmask_b32_e64 v151, 0, v151, s[6:7]
	v_cndmask_b32_e64 v155, 0, v155, s[8:9]
	v_cndmask_b32_e64 v152, 0, v152, s[10:11]
	v_cndmask_b32_e64 v156, 0, v156, s[12:13]
	v_add_f32_e32 v159, 0, v159
	v_add_f32_e32 v160, v151, v155
	v_add_f32_e32 v193, v152, v156
	v_cndmask_b32_e64 v194, 0, v153, s[14:15]
	v_cndmask_b32_e64 v149, 0, v149, s[16:17]
	v_add_f32_e32 v181, v160, v159
	v_pk_mul_f32 v[36:37], v[36:37], v[192:193] op_sel_hi:[1,0]
	v_pk_mul_f32 v[34:35], v[34:35], v[192:193] op_sel_hi:[1,0]
	v_cvt_pk_bf16_f32 v150, v150, v151
	v_cvt_pk_bf16_f32 v151, v152, v194
	v_cvt_pk_bf16_f32 v152, v154, v155
	v_cvt_pk_bf16_f32 v153, v156, v149
	ds_read_b64_tr_b16 v[188:189], v206 offset:0+0
	ds_read_b64_tr_b16 v[190:191], v206 offset:0+4352
	ds_read_b64_tr_b16 v[184:185], v206 offset:0+32
	ds_read_b64_tr_b16 v[186:187], v206 offset:0+4384
	ds_read_b64_tr_b16 v[158:159], v206 offset:0+64
	ds_read_b64_tr_b16 v[160:161], v206 offset:0+4416
	ds_read_b64_tr_b16 v[154:155], v206 offset:0+96
	ds_read_b64_tr_b16 v[156:157], v206 offset:0+4448
	ds_read_b64_tr_b16 v[240:241], v206 offset:128+0
	ds_read_b64_tr_b16 v[242:243], v206 offset:128+4352
	ds_read_b64_tr_b16 v[236:237], v206 offset:128+32
	ds_read_b64_tr_b16 v[238:239], v206 offset:128+4384
	ds_read_b64_tr_b16 v[232:233], v206 offset:128+64
	ds_read_b64_tr_b16 v[234:235], v206 offset:128+4416
	ds_read_b64_tr_b16 v[228:229], v206 offset:128+96
	ds_read_b64_tr_b16 v[230:231], v206 offset:128+4448
	s_waitcnt lgkmcnt(8)
	v_pk_mul_f32 v[20:21], v[20:21], v[192:193] op_sel_hi:[1,0]
	v_pk_mul_f32 v[18:19], v[18:19], v[192:193] op_sel_hi:[1,0]
	v_pk_mul_f32 v[24:25], v[24:25], v[192:193] op_sel_hi:[1,0]
	v_pk_mul_f32 v[22:23], v[22:23], v[192:193] op_sel_hi:[1,0]
	v_pk_mul_f32 v[28:29], v[28:29], v[192:193] op_sel_hi:[1,0]
	v_pk_mul_f32 v[26:27], v[26:27], v[192:193] op_sel_hi:[1,0]
	v_pk_mul_f32 v[32:33], v[32:33], v[192:193] op_sel_hi:[1,0]
	v_pk_mul_f32 v[30:31], v[30:31], v[192:193] op_sel_hi:[1,0]
	v_pk_mul_f32 v[40:41], v[40:41], v[192:193] op_sel_hi:[1,0]
	v_pk_mul_f32 v[38:39], v[38:39], v[192:193] op_sel_hi:[1,0]
	v_pk_mul_f32 v[48:49], v[48:49], v[192:193] op_sel_hi:[1,0]
	v_pk_mul_f32 v[46:47], v[46:47], v[192:193] op_sel_hi:[1,0]
	v_pk_mul_f32 v[56:57], v[56:57], v[192:193] op_sel_hi:[1,0]
	v_pk_mul_f32 v[54:55], v[54:55], v[192:193] op_sel_hi:[1,0]
	v_mfma_f32_16x16x32_bf16 v[34:37], v[188:191], v[150:153], v[34:37]
	v_add_f32_e32 v181, v193, v181
	v_add_f32_e32 v149, v194, v149
	v_add_f32_e32 v149, v149, v181
	v_mfma_f32_16x16x32_bf16 v[18:21], v[184:187], v[150:153], v[18:21]
	v_fmac_f32_e32 v149, v183, v192
	v_mfma_f32_16x16x32_bf16 v[22:25], v[158:161], v[150:153], v[22:25]
	v_mfma_f32_16x16x32_bf16 v[26:29], v[154:157], v[150:153], v[26:29]
	s_waitcnt lgkmcnt(0)
	s_nop 0
	v_mfma_f32_16x16x32_bf16 v[30:33], v[240:243], v[150:153], v[30:33]
	v_mfma_f32_16x16x32_bf16 v[38:41], v[236:239], v[150:153], v[38:41]
	v_mfma_f32_16x16x32_bf16 v[46:49], v[232:235], v[150:153], v[46:49]
	v_mfma_f32_16x16x32_bf16 v[54:57], v[228:231], v[150:153], v[54:57]
	s_cbranch_scc0 .LBB0_778
	v_mov_b32_e32 v227, v0
	v_mov_b32_e32 v183, v149
	s_branch .LBB0_807
